# A/B of the selected-stream per-stage issue priority: this version is the full stack WITHOUT it (no s_setprio in the stage loop); everything else as the previous best
# baseline (speedup 1.0000x reference)
; #define LAS __attribute__((address_space(3)))
; DEV void qk64(const LAS unsigned char* Kb, const AttnCtx& C, const ab8 (&qf)[2][2], f32x4 (&s)[2][4], float init0, float init1, bool a0, bool a1) {
;     ab8 k0[4], k1[4];
; #pragma unroll
;     for (int kt = 0; kt < 4; ++kt) { k0[kt] = *(const LAS ab8*)(Kb + swz(16 * kt + C.n, C.q4)); k1[kt] = *(const LAS ab8*)(Kb + swz(16 * kt + C.n, 4 + C.q4)); }
;     __builtin_amdgcn_sched_barrier(0);
; #pragma unroll
;     for (int kt = 0; kt < 4; ++kt) {
;         if (a0) { f32x4 c = {init0, init0, init0, init0}; c = __builtin_amdgcn_mfma_f32_16x16x32_bf16(k0[kt], qf[0][0], c, 0, 0, 0); s[0][kt] = __builtin_amdgcn_mfma_f32_16x16x32_bf16(k1[kt], qf[0][1], c, 0, 0, 0); }
;         if (a1) { f32x4 c = {init1, init1, init1, init1}; c = __builtin_amdgcn_mfma_f32_16x16x32_bf16(k0[kt], qf[1][0], c, 0, 0, 0); s[1][kt] = __builtin_amdgcn_mfma_f32_16x16x32_bf16(k1[kt], qf[1][1], c, 0, 0, 0); }
;     }
; }
; DEV void attn_unit_mfma(Frame& F, int qg, int kv) {
;     ...
;         const int j = lst[1 + i]; const unsigned byte = (msk[2 * j + (w >> 2)] >> (8 * (w & 3))) & 0xffu;
;         const bool a0 = (byte & 0xfu) != 0u, a1 = (byte & 0xf0u) != 0u;
;         if (a0 || a1) {
;             const bool near = j >= cur - 2; const float bi = near ? 0.f : C.b31;
;             const bool c0 = ((byte >> (C.n >> 2)) & 1u) != 0u, c1 = ((byte >> (4 + (C.n >> 2))) & 1u) != 0u;
;     ...
;             if (a0 && a1) SEL_BODY(true, true); else if (a0) SEL_BODY(true, false); else SEL_BODY(false, true);
.Lmy_sel_dma_done:
	s_waitcnt lgkmcnt(0)
	v_readfirstlane_b32 s9, v70
	v_readfirstlane_b32 s10, v71
	v_readfirstlane_b32 s11, v72
	s_and_b32 s34, s37, 0xffff
	s_lshr_b32 s9, s9, s33
	s_and_b32 s9, s9, 0xff
	s_lshl_b32 s9, s9, 16
	s_or_b32 s34, s34, s9
	s_and_b32 s35, s38, 0xffff
	s_lshr_b32 s10, s10, s33
	s_and_b32 s10, s10, 0xff
	s_lshl_b32 s10, s10, 16
	s_or_b32 s35, s35, s10
	s_and_b32 s36, s39, 0xffff
	s_lshr_b32 s11, s11, s33
	s_and_b32 s11, s11, 0xff
	s_lshl_b32 s11, s11, 16
	s_or_b32 s36, s36, s11
	v_readfirstlane_b32 s37, v73
	v_readfirstlane_b32 s38, v74
	v_readfirstlane_b32 s39, v75
.LBB0_1171:
	s_mul_i32 s8, s8, 0xc000
	s_add_i32 s9, s28, -2
	s_add_i32 s27, s8, 0
	s_cmp_ge_i32 s9, s23
	s_cbranch_scc1 .LBB0_1196
	s_waitcnt lgkmcnt(0)
	s_and_b32 s29, s98, 0xffff
	s_lshr_b32 s8, s98, 16
	s_and_b32 s9, s8, 0xff
	s_cmp_eq_u32 s9, 0
	s_cbranch_scc1 .LBB0_1196
	s_cmp_ge_i32 s29, s22
	s_cbranch_scc1 .Lmy_orig_0
	s_and_b32 s9, s8, 15
	s_and_b32 s10, s8, 0xf0
	s_cmp_lg_u32 s9, 0
	s_cselect_b32 s11, 1, 0
	s_cmp_lg_u32 s10, 0
	s_cselect_b32 s12, 1, 0
	s_add_i32 s13, s11, s12
	s_cmp_eq_u32 s13, 2
	s_cbranch_scc1 .Lmy_fb_0
	s_cmp_eq_u32 s11, 1
	s_cbranch_scc0 .Lmy_f1_0
	v_add3_u32 v228, s27, v199, v198
	v_add3_u32 v229, s27, v197, v198
	ds_read_b128 v[66:69], v228 offset:0
	ds_read_b128 v[70:73], v229 offset:0
	ds_read_b128 v[74:77], v228 offset:2048
	ds_read_b128 v[78:81], v229 offset:2048
	ds_read_b128 v[82:85], v228 offset:4096
	ds_read_b128 v[86:89], v229 offset:4096
	ds_read_b128 v[90:93], v228 offset:6144
	ds_read_b128 v[94:97], v229 offset:6144
	v_and_b32_e32 v239, s8, v206
	v_cmp_ne_u32_e64 s[10:11], 0, v239
	v_cmp_eq_f32_e64 s[12:13], s3, v213
	v_add_u32_e32 v234, s27, v200
	v_add3_u32 v235, v234, v201, v209
	v_add3_u32 v236, v234, v202, v209
	v_cndmask_b32_e64 v230, v213, 0, s[12:13]
	v_sub_f32_e32 v230, v175, v230
	v_add3_u32 v237, v234, v203, v209
	v_add3_u32 v238, v234, v204, v209
	v_cndmask_b32_e64 v230, v173, v230, s[10:11]
	v_mov_b32_e32 v231, v230
	v_mov_b32_e32 v232, v230
	v_mov_b32_e32 v233, v230
	s_and_b64 s[12:13], s[10:11], s[12:13]
	s_waitcnt lgkmcnt(0)
	v_mfma_f32_16x16x32_bf16 v[66:69], v[66:69], v[2:5], v[230:233]
	v_mfma_f32_16x16x32_bf16 v[74:77], v[74:77], v[2:5], v[230:233]
	v_mfma_f32_16x16x32_bf16 v[82:85], v[82:85], v[2:5], v[230:233]
	v_mfma_f32_16x16x32_bf16 v[90:93], v[90:93], v[2:5], v[230:233]
	v_mfma_f32_16x16x32_bf16 v[66:69], v[70:73], v[6:9], v[66:69]
	v_mfma_f32_16x16x32_bf16 v[74:77], v[78:81], v[6:9], v[74:77]
	v_mfma_f32_16x16x32_bf16 v[82:85], v[86:89], v[6:9], v[82:85]
	v_mfma_f32_16x16x32_bf16 v[90:93], v[94:97], v[6:9], v[90:93]
	ds_read_b64_tr_b16 v[98:99], v235 offset:8192
	ds_read_b64_tr_b16 v[100:101], v235 offset:10240
	ds_read_b64_tr_b16 v[102:103], v235 offset:12288
	ds_read_b64_tr_b16 v[104:105], v235 offset:14336
	ds_read_b64_tr_b16 v[106:107], v236 offset:8192
	ds_read_b64_tr_b16 v[108:109], v236 offset:10240
	ds_read_b64_tr_b16 v[110:111], v236 offset:12288
	ds_read_b64_tr_b16 v[112:113], v236 offset:14336
	ds_read_b64_tr_b16 v[114:115], v237 offset:8192
	ds_read_b64_tr_b16 v[116:117], v237 offset:10240
	ds_read_b64_tr_b16 v[118:119], v237 offset:12288
	ds_read_b64_tr_b16 v[120:121], v237 offset:14336
	ds_read_b64_tr_b16 v[122:123], v238 offset:8192
	ds_read_b64_tr_b16 v[124:125], v238 offset:10240
	ds_read_b64_tr_b16 v[126:127], v238 offset:12288
	ds_read_b64_tr_b16 v[128:129], v238 offset:14336
	v_max3_f32 v239, v66, v67, v68
	v_max3_f32 v240, v69, v74, v75
	v_max3_f32 v241, v76, v77, v82
	v_max3_f32 v242, v83, v84, v85
	v_max3_f32 v239, v239, v240, v90
	v_max3_f32 v241, v241, v242, v91
	v_max3_f32 v239, v239, v92, v93
	v_max_f32_e32 v239, v239, v241
	v_cmp_lt_f32_e32 vcc, s96, v239
	s_or_b64 s[12:13], s[12:13], vcc
	s_cmp_lg_u64 s[12:13], 0
	s_cbranch_scc1 .Lmy_slow_0_0
	v_exp_f32_e32 v66, v66
	v_exp_f32_e32 v67, v67
	v_exp_f32_e32 v68, v68
	v_exp_f32_e32 v69, v69
	v_exp_f32_e32 v74, v74
	v_exp_f32_e32 v75, v75
	v_exp_f32_e32 v76, v76
	v_exp_f32_e32 v77, v77
	v_exp_f32_e32 v82, v82
	v_exp_f32_e32 v83, v83
	v_exp_f32_e32 v84, v84
	v_exp_f32_e32 v85, v85
	v_exp_f32_e32 v90, v90
	v_exp_f32_e32 v91, v91
	v_exp_f32_e32 v92, v92
	v_exp_f32_e32 v93, v93
	v_cvt_pk_bf16_f32 v130, v66, v67
	v_cvt_pk_bf16_f32 v131, v68, v69
	v_cvt_pk_bf16_f32 v132, v74, v75
	v_cvt_pk_bf16_f32 v133, v76, v77
	v_cvt_pk_bf16_f32 v134, v82, v83
	v_cvt_pk_bf16_f32 v135, v84, v85
	v_cvt_pk_bf16_f32 v136, v90, v91
	v_cvt_pk_bf16_f32 v137, v92, v93
	s_nop 1
	s_waitcnt lgkmcnt(12)
	v_mfma_f32_16x16x32_bf16 v[62:65], v[98:101], v[130:133], v[62:65]
	v_mfma_f32_16x16x32_bf16 v[58:61], v[22:25], v[130:133], v[58:61]
	v_mfma_f32_16x16x32_bf16 v[62:65], v[102:105], v[134:137], v[62:65]
	s_waitcnt lgkmcnt(8)
	v_mfma_f32_16x16x32_bf16 v[54:57], v[106:109], v[130:133], v[54:57]
	v_mfma_f32_16x16x32_bf16 v[54:57], v[110:113], v[134:137], v[54:57]
	s_waitcnt lgkmcnt(4)
	v_mfma_f32_16x16x32_bf16 v[50:53], v[114:117], v[130:133], v[50:53]
	v_mfma_f32_16x16x32_bf16 v[58:61], v[22:25], v[134:137], v[58:61]
	v_mfma_f32_16x16x32_bf16 v[50:53], v[118:121], v[134:137], v[50:53]
	s_waitcnt lgkmcnt(0)
	v_mfma_f32_16x16x32_bf16 v[46:49], v[122:125], v[130:133], v[46:49]
	v_mfma_f32_16x16x32_bf16 v[46:49], v[126:129], v[134:137], v[46:49]
	s_nop 7
	s_branch .LBB0_1196
